# 64-lane sum finish via row_bcast dpp adds + one readlane (16 sites in P7), plus 23 more fused dpp reduction steps
# speedup vs baseline: 1.0859x; 1.0042x over previous
; __device__ __forceinline__ unsigned pk2(float lo, float hi) { const f32x2 v = {lo, hi}; const bf16x2_t b = __builtin_convertvector(v, bf16x2_t); return __builtin_bit_cast(unsigned, b); }
; __device__ __forceinline__ void phase0(const Ctx& C) {
;     ...
;     for (int row = gw; row < T_; row += 4 * NGW) {
;         f32x4 v[4][4];
; #pragma unroll
;         for (int r = 0; r < 4; ++r) { const int rw = (row + r * NGW < T_) ? row + r * NGW : row; const f32x4* xa = (const f32x4*)(x + (size_t)rw * D_) + lane;
; #pragma unroll
;             for (int j = 0; j < 4; ++j) v[r][j] = xa[64 * j]; }
; #pragma unroll
;         for (int r = 0; r < 4; ++r) {
;             const int rw = row + r * NGW; const bool has = rw < T_;
;             float s = 0.f; u32x2* oa = (u32x2*)(xb + (size_t)(has ? rw : row) * D_) + lane;
; #pragma unroll
;             for (int j = 0; j < 4; ++j) {
;                 s += (v[r][j][0] * v[r][j][0] + v[r][j][1] * v[r][j][1]) + (v[r][j][2] * v[r][j][2] + v[r][j][3] * v[r][j][3]);
;                 if (has) { u32x2 w; w.x = pk2(v[r][j][0], v[r][j][1]); w.y = pk2(v[r][j][2], v[r][j][3]); oa[64 * j] = w; }
;             }
;             s = wave_sum(s);
;             if (has && lane < 16) ssq[(size_t)rw * 16 + lane] = lane == 0 ? s : 0.f;
.LBB0_156:
	s_ashr_i32 s11, s10, 31
	s_lshl_b64 s[4:5], s[10:11], 12
	s_add_i32 s14, s10, s0
	s_cmpk_lt_i32 s14, 0x4000
	s_waitcnt lgkmcnt(0)
	s_cselect_b64 s[42:43], -1, 0
	v_lshl_add_u64 v[2:3], v[50:51], 0, s[4:5]
	s_and_b64 s[4:5], s[42:43], exec
	s_cselect_b32 s44, s14, s10
	global_load_dwordx4 v[56:59], v[2:3], off
	global_load_dwordx4 v[60:63], v[2:3], off offset:1024
	global_load_dwordx4 v[64:67], v[2:3], off offset:2048
	global_load_dwordx4 v[68:71], v[2:3], off offset:3072
	s_ashr_i32 s45, s44, 31
	s_add_i32 s18, s1, s10
	s_lshl_b64 s[4:5], s[44:45], 12
	s_cmpk_lt_i32 s18, 0x4000
	s_cselect_b64 s[36:37], -1, 0
	v_lshl_add_u64 v[2:3], v[50:51], 0, s[4:5]
	s_and_b64 s[4:5], s[36:37], exec
	s_cselect_b32 s40, s18, s10
	s_ashr_i32 s41, s40, 31
	s_add_i32 s16, s2, s10
	s_lshl_b64 s[4:5], s[40:41], 12
	s_cmpk_lt_i32 s16, 0x4000
	s_cselect_b64 s[20:21], -1, 0
	global_load_dwordx4 v[46:49], v[2:3], off
	global_load_dwordx4 v[42:45], v[2:3], off offset:1024
	global_load_dwordx4 v[38:41], v[2:3], off offset:2048
	global_load_dwordx4 v[34:37], v[2:3], off offset:3072
	v_lshl_add_u64 v[2:3], v[50:51], 0, s[4:5]
	s_and_b64 s[4:5], s[20:21], exec
	s_cselect_b32 s22, s16, s10
	s_ashr_i32 s23, s22, 31
	s_lshl_b64 s[4:5], s[22:23], 12
	global_load_dwordx4 v[30:33], v[2:3], off
	global_load_dwordx4 v[26:29], v[2:3], off offset:1024
	global_load_dwordx4 v[22:25], v[2:3], off offset:2048
	global_load_dwordx4 v[18:21], v[2:3], off offset:3072
	v_lshl_add_u64 v[2:3], v[50:51], 0, s[4:5]
	global_load_dwordx4 v[14:17], v[2:3], off
	global_load_dwordx4 v[10:13], v[2:3], off offset:1024
	global_load_dwordx4 v[6:9], v[2:3], off offset:2048
	s_nop 0
	global_load_dwordx4 v[2:5], v[2:3], off offset:3072
	s_lshl_b64 s[4:5], s[10:11], 11
	v_lshl_add_u64 v[72:73], v[52:53], 0, s[4:5]
	s_waitcnt vmcnt(15)
	v_mul_f32_e32 v1, v57, v57
	v_mul_f32_e32 v82, v59, v59
	v_cvt_pk_bf16_f32 v74, v56, v57
	v_cvt_pk_bf16_f32 v75, v58, v59
	s_waitcnt vmcnt(14)
	v_mul_f32_e32 v57, v61, v61
	v_mul_f32_e32 v59, v63, v63
	v_cvt_pk_bf16_f32 v76, v60, v61
	v_cvt_pk_bf16_f32 v77, v62, v63
	s_waitcnt vmcnt(13)
	v_mul_f32_e32 v61, v65, v65
	v_mul_f32_e32 v63, v67, v67
	v_fmac_f32_e32 v1, v56, v56
	v_fmac_f32_e32 v82, v58, v58
	v_fmac_f32_e32 v57, v60, v60
	v_fmac_f32_e32 v59, v62, v62
	v_cvt_pk_bf16_f32 v78, v64, v65
	v_cvt_pk_bf16_f32 v79, v66, v67
	s_waitcnt vmcnt(12)
	v_mul_f32_e32 v65, v69, v69
	v_mul_f32_e32 v67, v71, v71
	v_fmac_f32_e32 v61, v64, v64
	v_fmac_f32_e32 v63, v66, v66
	v_add_f32_e32 v1, v1, v82
	v_add_f32_e32 v56, v57, v59
	v_fmac_f32_e32 v65, v68, v68
	v_fmac_f32_e32 v67, v70, v70
	v_add_f32_e32 v57, v61, v63
	v_add_f32_e32 v1, v1, v56
	v_add_f32_e32 v58, v65, v67
	v_add_f32_e32 v1, v1, v57
	v_add_f32_e32 v1, v1, v58
	v_cvt_pk_bf16_f32 v80, v68, v69
	v_cvt_pk_bf16_f32 v81, v70, v71
	s_nop 1
	v_add_f32_dpp v1, v1, v1 quad_perm:[1,0,3,2] row_mask:0xf bank_mask:0xf
	global_store_dwordx2 v[72:73], v[74:75], off
	global_store_dwordx2 v[72:73], v[76:77], off offset:512
	s_nop 1
	v_add_f32_dpp v1, v1, v1 quad_perm:[2,3,0,1] row_mask:0xf bank_mask:0xf
	global_store_dwordx2 v[72:73], v[78:79], off offset:1024
	global_store_dwordx2 v[72:73], v[80:81], off offset:1536
	s_nop 1
	v_add_f32_dpp v1, v1, v1 row_half_mirror row_mask:0xf bank_mask:0xf
	s_nop 1
	v_add_f32_dpp v1, v1, v1 row_mirror row_mask:0xf bank_mask:0xf
	s_nop 0
	v_readlane_b32 s60, v1, 0
	v_readlane_b32 s3, v1, 16
	v_readlane_b32 s61, v1, 32
	v_readlane_b32 s4, v1, 48
	s_and_saveexec_b64 s[56:57], s[6:7]
	s_cbranch_execz .LBB0_158
	v_mov_b32_e32 v58, s3
	v_mov_b32_e32 v59, s4
	v_pk_add_f32 v[58:59], s[60:61], v[58:59]
	s_lshl_b64 s[10:11], s[10:11], 6
	v_add_f32_e32 v1, v58, v59
	v_lshl_add_u64 v[56:57], v[54:55], 0, s[10:11]
	v_cndmask_b32_e64 v1, 0, v1, s[8:9]
	global_store_dword v[56:57], v1, off

; __device__ __forceinline__ float wave_sum(float v) {
;     v += dpp_f(v, 0); v += dpp_f(v, 1); v += dpp_f(v, 2); v += dpp_f(v, 3);
;     const int vi = __float_as_int(v);
;     const float s0 = __int_as_float(__builtin_amdgcn_readlane(vi, 0)), s1 = __int_as_float(__builtin_amdgcn_readlane(vi, 16)), s2 = __int_as_float(__builtin_amdgcn_readlane(vi, 32)), s3 = __int_as_float(__builtin_amdgcn_readlane(vi, 48));
;     return (s0 + s1) + (s2 + s3);
; __device__ __forceinline__ void rwkv_phase_a(const Ctx& C) {
;     ...
;             for (int u = 0; u < 8; ++u) {
;                 const int t = tg8 * 8 + u;
;                 ld[u] = FM(0)[t * MS + ci]; av[u] = FM(1)[t * MS + ci];
;                 const float kr = kx[u] * kkc; const float n2 = wave_sum(kr * kr);
;                 kkv[u] = kr * __builtin_amdgcn_rsqf(fmaxf(n2, 1e-24f));
;                 k2[u] = kx[u] * (1.0f + (av[u] - 1.0f) * kac);
;                 const float bs = wave_sum(rr[u] * k2[u] * rkc);
;                 if (lane == 0) bon[(size_t)(tok0 + t) * 8 + h] = bs;
;                 run += ld[u]; cl[u] = run;
.LBB0_723:
	s_or_b64 exec, exec, s[22:23]
	v_lshlrev_b32_e32 v103, 16, v227
	v_sub_f32_e32 v99, v99, v103
	v_and_b32_e32 v106, 0xffff0000, v228
	v_fma_f32 v139, v223, v99, v103
	v_sub_f32_e32 v99, v102, v106
	v_fma_f32 v99, v222, v99, v106
	v_mul_f32_e32 v128, v99, v125
	v_mul_f32_e32 v102, v128, v128
	v_or_b32_e32 v140, 1, v212
	v_mad_u64_u32 v[104:105], s[14:15], v140, s97, v[192:193]
	v_mov_b32_dpp v102, v102 quad_perm:[1,0,3,2] row_mask:0xf bank_mask:0xf
	v_fmac_f32_e32 v102, v128, v128
	v_lshl_add_u32 v120, v104, 2, 0
	ds_read2st64_b32 v[104:105], v120 offset1:68
	s_nop 1
	v_add_f32_dpp v102, v102, v102 quad_perm:[2,3,0,1] row_mask:0xf bank_mask:0xf
	s_nop 1
	v_add_f32_dpp v102, v102, v102 row_half_mirror row_mask:0xf bank_mask:0xf
	s_nop 1
	v_add_f32_dpp v102, v102, v102 row_mirror row_mask:0xf bank_mask:0xf
	s_nop 0
	v_readlane_b32 s49, v102, 0
	v_readlane_b32 s74, v102, 16
	v_readlane_b32 s73, v102, 32
	v_readlane_b32 s75, v102, 48
	s_waitcnt lgkmcnt(0)
	v_add_f32_e32 v102, -1.0, v105
	v_fma_f32 v102, v117, v102, 1.0
	v_mul_f32_e32 v99, v99, v102
	v_mul_f32_e32 v102, v139, v99
	v_mul_f32_e32 v107, v124, v102
	s_nop 1
	v_mov_b32_dpp v107, v107 quad_perm:[1,0,3,2] row_mask:0xf bank_mask:0xf
	v_fmac_f32_e32 v107, v124, v102
	s_nop 1
	v_add_f32_dpp v102, v107, v107 quad_perm:[2,3,0,1] row_mask:0xf bank_mask:0xf
	s_nop 1
	v_add_f32_dpp v102, v102, v102 row_half_mirror row_mask:0xf bank_mask:0xf
	s_nop 1
	v_add_f32_dpp v102, v102, v102 row_mirror row_mask:0xf bank_mask:0xf
	s_nop 0
	v_readlane_b32 s44, v102, 0
	v_readlane_b32 s14, v102, 16
	v_readlane_b32 s45, v102, 32
	v_readlane_b32 s15, v102, 48
	s_and_saveexec_b64 s[22:23], vcc
	s_cbranch_execz .LBB0_725
	v_add_u32_e32 v108, s61, v212
	v_ashrrev_i32_e32 v109, 31, v108
	s_add_u32 s42, s26, s16
	v_mov_b32_e32 v110, s14
	v_mov_b32_e32 v111, s15
	v_lshlrev_b64 v[108:109], 5, v[108:109]
	s_addc_u32 s43, s27, s17
	v_pk_add_f32 v[110:111], s[44:45], v[110:111]
	v_lshl_add_u64 v[108:109], s[42:43], 0, v[108:109]
	v_add_f32_e32 v102, v110, v111
	global_store_dword v[108:109], v102, off

; __device__ __forceinline__ float wave_sum(float v) {
;     v += dpp_f(v, 0); v += dpp_f(v, 1); v += dpp_f(v, 2); v += dpp_f(v, 3);
;     const int vi = __float_as_int(v);
;     const float s0 = __int_as_float(__builtin_amdgcn_readlane(vi, 0)), s1 = __int_as_float(__builtin_amdgcn_readlane(vi, 16)), s2 = __int_as_float(__builtin_amdgcn_readlane(vi, 32)), s3 = __int_as_float(__builtin_amdgcn_readlane(vi, 48));
;     return (s0 + s1) + (s2 + s3);
; __device__ __forceinline__ void rwkv_phase_a(const Ctx& C) {
;     ...
;             for (int u = 0; u < 8; ++u) {
;                 const int t = tg8 * 8 + u;
;                 ld[u] = FM(0)[t * MS + ci]; av[u] = FM(1)[t * MS + ci];
;                 const float kr = kx[u] * kkc; const float n2 = wave_sum(kr * kr);
;                 kkv[u] = kr * __builtin_amdgcn_rsqf(fmaxf(n2, 1e-24f));
;                 k2[u] = kx[u] * (1.0f + (av[u] - 1.0f) * kac);
;                 const float bs = wave_sum(rr[u] * k2[u] * rkc);
;                 if (lane == 0) bon[(size_t)(tok0 + t) * 8 + h] = bs;
;                 run += ld[u]; cl[u] = run;
.LBB0_727:
	s_or_b64 exec, exec, s[22:23]
	v_and_b32_e32 v111, 0xffff0000, v226
	v_sub_f32_e32 v103, v103, v111
	v_fma_f32 v103, v222, v103, v111
	v_mul_f32_e32 v130, v103, v125
	v_mul_f32_e32 v112, v130, v130
	v_lshlrev_b32_e32 v110, 16, v225
	v_sub_f32_e32 v108, v108, v110
	v_mov_b32_dpp v112, v112 quad_perm:[1,0,3,2] row_mask:0xf bank_mask:0xf
	v_fmac_f32_e32 v112, v130, v130
	v_fma_f32 v142, v223, v108, v110
	v_add_u32_e32 v108, 32, v120
	s_nop 1
	v_add_f32_dpp v112, v112, v112 quad_perm:[2,3,0,1] row_mask:0xf bank_mask:0xf
	ds_read2st64_b32 v[108:109], v108 offset0:2 offset1:70
	s_nop 0
	s_nop 1
	v_add_f32_dpp v112, v112, v112 row_half_mirror row_mask:0xf bank_mask:0xf
	s_nop 1
	v_add_f32_dpp v112, v112, v112 row_mirror row_mask:0xf bank_mask:0xf
	s_nop 0
	v_readlane_b32 s80, v112, 0
	v_readlane_b32 s14, v112, 16
	v_readlane_b32 s81, v112, 32
	v_readlane_b32 s15, v112, 48
	s_waitcnt lgkmcnt(0)
	v_add_f32_e32 v112, -1.0, v109
	v_fma_f32 v112, v117, v112, 1.0
	v_mul_f32_e32 v103, v103, v112
	v_mul_f32_e32 v112, v142, v103
	v_mul_f32_e32 v113, v124, v112
	s_nop 1
	v_mov_b32_dpp v113, v113 quad_perm:[1,0,3,2] row_mask:0xf bank_mask:0xf
	v_fmac_f32_e32 v113, v124, v112
	s_nop 1
	v_add_f32_dpp v112, v113, v113 quad_perm:[2,3,0,1] row_mask:0xf bank_mask:0xf
	s_nop 1
	v_add_f32_dpp v112, v112, v112 row_half_mirror row_mask:0xf bank_mask:0xf
	s_nop 1
	v_add_f32_dpp v112, v112, v112 row_mirror row_mask:0xf bank_mask:0xf
	s_nop 0
	v_readlane_b32 s44, v112, 0
	v_readlane_b32 s42, v112, 16
	v_readlane_b32 s45, v112, 32
	v_readlane_b32 s43, v112, 48
	s_and_saveexec_b64 s[22:23], vcc
	s_cbranch_execz .LBB0_729
	v_add_u32_e32 v112, s63, v212
	v_ashrrev_i32_e32 v113, 31, v112
	s_add_u32 s52, s26, s16
	v_mov_b32_e32 v114, s42
	v_mov_b32_e32 v115, s43
	v_lshlrev_b64 v[112:113], 5, v[112:113]
	s_addc_u32 s53, s27, s17
	v_pk_add_f32 v[114:115], s[44:45], v[114:115]
	v_lshl_add_u64 v[112:113], s[52:53], 0, v[112:113]
	v_add_f32_e32 v114, v114, v115
	global_store_dword v[112:113], v114, off

; __device__ __forceinline__ bf16_t f2bf(float f) { return (bf16_t)(pk2(f, 0.f) & 0xffffu); }
; __device__ __forceinline__ float wave_sum(float v) {
;     v += dpp_f(v, 0); v += dpp_f(v, 1); v += dpp_f(v, 2); v += dpp_f(v, 3);
;     const int vi = __float_as_int(v);
;     const float s0 = __int_as_float(__builtin_amdgcn_readlane(vi, 0)), s1 = __int_as_float(__builtin_amdgcn_readlane(vi, 16)), s2 = __int_as_float(__builtin_amdgcn_readlane(vi, 32)), s3 = __int_as_float(__builtin_amdgcn_readlane(vi, 48));
;     return (s0 + s1) + (s2 + s3);
; __device__ __forceinline__ void rwkv_phase_c(const Ctx& C) {
;     ...
;             for (int u = 0; u < 8; ++u) {
;                 const int t = tg8 * 8 + u, tok = tok0 + t;
;                 const float y = MAT(1)[t * MS + ci];
;                 const float mean = wave_sum(y) * (1.0f / 64.0f); const float dlt = y - mean;
;                 const float var = wave_sum(dlt * dlt) * (1.0f / 64.0f);
;                 const float yn = dlt * (1.0f / sqrtf(var + 64e-5f)) * gg + gb;
;                 ycat[(size_t)tok * D_ + h * 64 + ci] = f2bf((yn + bo[u] * vv[u]) * gt[u]);
;             }
.LBB0_1062:
	v_cmp_lt_i32_e32 vcc, 0, v42
	s_waitcnt vmcnt(31)
	v_lshlrev_b32_e32 v12, 16, v94
	s_waitcnt vmcnt(30)
	v_lshlrev_b32_e32 v2, 16, v93
	v_cndmask_b32_e64 v3, 0, 1.0, vcc
	v_fma_f32 v2, v3, v2, -v12
	v_cmp_lt_i32_e32 vcc, -1, v42
	v_fmac_f32_e32 v12, v52, v2
	s_waitcnt vmcnt(28)
	v_lshlrev_b32_e32 v13, 16, v91
	s_waitcnt vmcnt(27)
	v_lshlrev_b32_e32 v91, 16, v92
	s_waitcnt vmcnt(26)
	v_lshlrev_b32_e32 v2, 16, v90
	v_cndmask_b32_e64 v3, 0, 1.0, vcc
	v_fma_f32 v2, v3, v2, -v91
	v_fmac_f32_e32 v91, v52, v2
	s_waitcnt vmcnt(23)
	v_lshlrev_b32_e32 v90, 16, v103
	s_waitcnt vmcnt(22)
	v_lshlrev_b32_e32 v2, 16, v104
	v_fma_f32 v2, v3, v2, -v90
	v_fmac_f32_e32 v90, v52, v2
	s_waitcnt vmcnt(19)
	v_lshlrev_b32_e32 v93, 16, v98
	s_waitcnt vmcnt(18)
	v_lshlrev_b32_e32 v2, 16, v99
	v_fma_f32 v2, v3, v2, -v93
	v_fmac_f32_e32 v93, v52, v2
	s_waitcnt vmcnt(16)
	v_lshlrev_b32_e32 v94, 16, v96
	s_waitcnt vmcnt(15)
	v_lshlrev_b32_e32 v8, 16, v109
	s_waitcnt vmcnt(14)
	v_lshlrev_b32_e32 v2, 16, v110
	v_add_u32_e32 v96, 0x4400, v79
	v_fma_f32 v2, v3, v2, -v8
	ds_read2_b32 v[10:11], v96 offset1:68
	v_fmac_f32_e32 v8, v52, v2
	s_waitcnt vmcnt(11)
	v_lshlrev_b32_e32 v6, 16, v107
	s_waitcnt vmcnt(10)
	v_lshlrev_b32_e32 v2, 16, v108
	v_fma_f32 v2, v3, v2, -v6
	v_fmac_f32_e32 v6, v52, v2
	s_waitcnt vmcnt(7)
	v_lshlrev_b32_e32 v4, 16, v111
	s_waitcnt vmcnt(6)
	v_lshlrev_b32_e32 v2, 16, v112
	v_fma_f32 v2, v3, v2, -v4
	v_fmac_f32_e32 v4, v52, v2
	s_waitcnt lgkmcnt(0)
	v_lshlrev_b32_e32 v92, 16, v97
	s_waitcnt vmcnt(2)
	v_lshlrev_b32_e32 v99, 16, v102
	s_nop 1
	v_add_f32_dpp v2, v10, v10 quad_perm:[1,0,3,2] row_mask:0xf bank_mask:0xf
	v_lshlrev_b32_e32 v89, 16, v89
	v_lshlrev_b32_e32 v9, 16, v106
	s_nop 1
	v_add_f32_dpp v2, v2, v2 quad_perm:[2,3,0,1] row_mask:0xf bank_mask:0xf
	v_lshlrev_b32_e32 v7, 16, v105
	s_add_i32 s51, s51, 1
	s_nop 1
	v_add_f32_dpp v2, v2, v2 row_half_mirror row_mask:0xf bank_mask:0xf
	s_add_i32 s10, s10, 8
	s_nop 0
	s_nop 1
	v_add_f32_dpp v2, v2, v2 row_mirror row_mask:0xf bank_mask:0xf
	s_nop 0
	s_nop 1
	v_add_f32_dpp v2, v2, v2 row_bcast:15 row_mask:0xa bank_mask:0xf
	s_nop 1
	v_add_f32_dpp v2, v2, v2 row_bcast:31 row_mask:0xc bank_mask:0xf
	s_nop 1
	v_readlane_b32 s6, v2, 63
	v_mov_b32_e32 v2, s6
	v_fmamk_f32 v10, v2, 0xbc800000, v10
	v_mul_f32_e32 v2, v10, v10
	s_nop 1
	v_mov_b32_dpp v2, v2 quad_perm:[1,0,3,2] row_mask:0xf bank_mask:0xf
	v_fmac_f32_e32 v2, v10, v10
	s_nop 1
	v_add_f32_dpp v2, v2, v2 quad_perm:[2,3,0,1] row_mask:0xf bank_mask:0xf
	s_nop 1
	v_add_f32_dpp v2, v2, v2 row_half_mirror row_mask:0xf bank_mask:0xf
	s_nop 1
	v_add_f32_dpp v2, v2, v2 row_mirror row_mask:0xf bank_mask:0xf
	s_nop 0
	s_nop 1
	v_add_f32_dpp v2, v2, v2 row_bcast:15 row_mask:0xa bank_mask:0xf
	s_nop 1
	v_add_f32_dpp v2, v2, v2 row_bcast:31 row_mask:0xc bank_mask:0xf
	s_nop 1
	v_readlane_b32 s6, v2, 63
	v_mov_b32_e32 v2, s6
	v_fmamk_f32 v2, v2, 0x3c800000, v1
	v_mul_f32_e32 v5, 0x4f800000, v2
	v_cmp_gt_f32_e32 vcc, s48, v2
	s_nop 1
	v_cndmask_b32_e32 v97, v2, v5, vcc
	v_sqrt_f32_e32 v98, v97
	v_lshlrev_b32_e32 v5, 16, v100
	v_lshlrev_b32_e32 v2, 16, v101
	v_fma_f32 v3, v3, v99, -v2
	v_add_u32_e32 v100, -1, v98
	v_fma_f32 v101, -v100, v98, v97
	v_cmp_ge_f32_e64 s[6:7], 0, v101
	v_add_u32_e32 v101, 1, v98
	v_fmac_f32_e32 v2, v52, v3
	v_cndmask_b32_e64 v100, v98, v100, s[6:7]
	v_fma_f32 v98, -v101, v98, v97
	v_cmp_lt_f32_e64 s[6:7], 0, v98
	s_waitcnt vmcnt(0)
	v_lshlrev_b32_e32 v3, 16, v95
	v_cndmask_b32_e64 v98, v100, v101, s[6:7]
	v_mul_f32_e32 v100, 0x37800000, v98
	v_cndmask_b32_e32 v98, v98, v100, vcc
	v_cmp_class_f32_e32 vcc, v97, v44
	s_nop 1
	v_cndmask_b32_e32 v97, v98, v97, vcc
	v_div_scale_f32 v98, s[6:7], v97, v97, 1.0
	v_rcp_f32_e32 v100, v98
	s_nop 0
	v_fma_f32 v95, -v98, v100, 1.0
	v_fmac_f32_e32 v100, v95, v100
	v_div_scale_f32 v95, vcc, 1.0, v97, 1.0
	v_mul_f32_e32 v99, v95, v100
	v_fma_f32 v101, -v98, v99, v95
	v_fmac_f32_e32 v99, v101, v100
	v_fma_f32 v95, -v98, v99, v95
	v_div_fmas_f32 v95, v95, v100, v99
	v_div_fixup_f32 v95, v95, v97, 1.0
	v_mul_f32_e32 v10, v10, v95
	v_fma_f32 v10, v50, v10, v51
	v_fmac_f32_e32 v10, v88, v12
	s_nop 1
	v_add_f32_dpp v95, v11, v11 quad_perm:[1,0,3,2] row_mask:0xf bank_mask:0xf
	v_mul_f32_e32 v10, v10, v13
	v_cvt_pk_bf16_f32 v10, v10, s0
	s_nop 1
	v_add_f32_dpp v95, v95, v95 quad_perm:[2,3,0,1] row_mask:0xf bank_mask:0xf
	s_nop 1
	v_add_f32_dpp v95, v95, v95 row_half_mirror row_mask:0xf bank_mask:0xf
	s_nop 1
	v_add_f32_dpp v95, v95, v95 row_mirror row_mask:0xf bank_mask:0xf
	s_nop 0
	s_nop 1
	v_add_f32_dpp v95, v95, v95 row_bcast:15 row_mask:0xa bank_mask:0xf
	s_nop 1
	v_add_f32_dpp v95, v95, v95 row_bcast:31 row_mask:0xc bank_mask:0xf
	s_nop 1
	v_readlane_b32 s6, v95, 63
	v_mov_b32_e32 v95, s6
	v_fmac_f32_e32 v11, 0xbc800000, v95
	v_mul_f32_e32 v95, v11, v11
	s_nop 1
	v_mov_b32_dpp v95, v95 quad_perm:[1,0,3,2] row_mask:0xf bank_mask:0xf
	v_fmac_f32_e32 v95, v11, v11
	s_nop 1
	v_add_f32_dpp v95, v95, v95 quad_perm:[2,3,0,1] row_mask:0xf bank_mask:0xf
	s_nop 1
	v_add_f32_dpp v95, v95, v95 row_half_mirror row_mask:0xf bank_mask:0xf
	s_nop 1
	v_add_f32_dpp v95, v95, v95 row_mirror row_mask:0xf bank_mask:0xf
	s_nop 0
	s_nop 1
	v_add_f32_dpp v95, v95, v95 row_bcast:15 row_mask:0xa bank_mask:0xf
	s_nop 1
	v_add_f32_dpp v95, v95, v95 row_bcast:31 row_mask:0xc bank_mask:0xf
	s_nop 1
	v_readlane_b32 s6, v95, 63
	v_mov_b32_e32 v95, s6
	v_fmamk_f32 v95, v95, 0x3c800000, v1
	v_mul_f32_e32 v97, 0x4f800000, v95
	v_cmp_gt_f32_e32 vcc, s48, v95
	s_nop 1
	v_cndmask_b32_e32 v95, v95, v97, vcc
	v_sqrt_f32_e32 v97, v95
	s_nop 0
	v_add_u32_e32 v12, -1, v97
	v_fma_f32 v13, -v12, v97, v95
	v_cmp_ge_f32_e64 s[6:7], 0, v13
	v_add_u32_e32 v13, 1, v97
	v_fma_f32 v88, -v13, v97, v95
	v_cndmask_b32_e64 v12, v97, v12, s[6:7]
	v_cmp_lt_f32_e64 s[6:7], 0, v88
	s_nop 1
	v_cndmask_b32_e64 v12, v12, v13, s[6:7]
	v_mul_f32_e32 v13, 0x37800000, v12
	v_cndmask_b32_e32 v12, v12, v13, vcc
	v_cmp_class_f32_e32 vcc, v95, v44
	s_nop 1
	v_cndmask_b32_e32 v88, v12, v95, vcc
	v_div_scale_f32 v95, s[6:7], v88, v88, 1.0
	v_rcp_f32_e32 v97, v95
	v_lshlrev_b64 v[12:13], 11, v[42:43]
	v_lshl_add_u64 v[12:13], v[22:23], 0, v[12:13]
	global_store_short v[12:13], v10, off
	v_fma_f32 v10, -v95, v97, 1.0
	v_fmac_f32_e32 v97, v10, v97
	v_div_scale_f32 v10, vcc, 1.0, v88, 1.0
	v_mul_f32_e32 v42, v10, v97
	v_fma_f32 v12, -v95, v42, v10
	v_fmac_f32_e32 v42, v12, v97
	ds_read2_b32 v[12:13], v96 offset0:136 offset1:204
	v_fma_f32 v10, -v95, v42, v10
	v_div_fmas_f32 v10, v10, v97, v42
	v_div_fixup_f32 v10, v10, v88, 1.0
	v_mul_f32_e32 v10, v11, v10
	s_waitcnt lgkmcnt(0)
; __device__ __forceinline__ bf16_t f2bf(float f) { return (bf16_t)(pk2(f, 0.f) & 0xffffu); }
; __device__ __forceinline__ float wave_sum(float v) {
;     v += dpp_f(v, 0); v += dpp_f(v, 1); v += dpp_f(v, 2); v += dpp_f(v, 3);
;     const int vi = __float_as_int(v);
;     const float s0 = __int_as_float(__builtin_amdgcn_readlane(vi, 0)), s1 = __int_as_float(__builtin_amdgcn_readlane(vi, 16)), s2 = __int_as_float(__builtin_amdgcn_readlane(vi, 32)), s3 = __int_as_float(__builtin_amdgcn_readlane(vi, 48));
;     return (s0 + s1) + (s2 + s3);
; __device__ __forceinline__ void rwkv_phase_c(const Ctx& C) {
;     ...
;             for (int u = 0; u < 8; ++u) {
;                 const int t = tg8 * 8 + u, tok = tok0 + t;
;                 const float y = MAT(1)[t * MS + ci];
;                 const float mean = wave_sum(y) * (1.0f / 64.0f); const float dlt = y - mean;
;                 const float var = wave_sum(dlt * dlt) * (1.0f / 64.0f);
;                 const float yn = dlt * (1.0f / sqrtf(var + 64e-5f)) * gg + gb;
;                 ycat[(size_t)tok * D_ + h * 64 + ci] = f2bf((yn + bo[u] * vv[u]) * gt[u]);
;             }
	v_fma_f32 v10, v50, v10, v51
	v_fmac_f32_e32 v10, v87, v91
	s_nop 1
	v_add_f32_dpp v11, v12, v12 quad_perm:[1,0,3,2] row_mask:0xf bank_mask:0xf
	v_mul_f32_e32 v10, v10, v89
	v_cvt_pk_bf16_f32 v43, v10, s0
	s_nop 1
	v_add_f32_dpp v11, v11, v11 quad_perm:[2,3,0,1] row_mask:0xf bank_mask:0xf
	s_nop 1
	v_add_f32_dpp v11, v11, v11 row_half_mirror row_mask:0xf bank_mask:0xf
	s_nop 1
	v_add_f32_dpp v11, v11, v11 row_mirror row_mask:0xf bank_mask:0xf
	s_nop 0
	s_nop 1
	v_add_f32_dpp v11, v11, v11 row_bcast:15 row_mask:0xa bank_mask:0xf
	s_nop 1
	v_add_f32_dpp v11, v11, v11 row_bcast:31 row_mask:0xc bank_mask:0xf
	s_nop 1
	v_readlane_b32 s6, v11, 63
	v_mov_b32_e32 v11, s6
	v_fmamk_f32 v12, v11, 0xbc800000, v12
	v_mul_f32_e32 v11, v12, v12
	s_nop 1
	v_mov_b32_dpp v11, v11 quad_perm:[1,0,3,2] row_mask:0xf bank_mask:0xf
	v_fmac_f32_e32 v11, v12, v12
	s_nop 1
	v_add_f32_dpp v11, v11, v11 quad_perm:[2,3,0,1] row_mask:0xf bank_mask:0xf
	s_nop 1
	v_add_f32_dpp v11, v11, v11 row_half_mirror row_mask:0xf bank_mask:0xf
	s_nop 1
	v_add_f32_dpp v11, v11, v11 row_mirror row_mask:0xf bank_mask:0xf
	s_nop 0
	s_nop 1
	v_add_f32_dpp v11, v11, v11 row_bcast:15 row_mask:0xa bank_mask:0xf
	s_nop 1
	v_add_f32_dpp v11, v11, v11 row_bcast:31 row_mask:0xc bank_mask:0xf
	s_nop 1
	v_readlane_b32 s6, v11, 63
	v_mov_b32_e32 v11, s6
	v_fmamk_f32 v11, v11, 0x3c800000, v1
	v_mul_f32_e32 v42, 0x4f800000, v11
	v_cmp_gt_f32_e32 vcc, s48, v11
	s_nop 1
	v_cndmask_b32_e32 v11, v11, v42, vcc
	v_sqrt_f32_e32 v42, v11
	s_nop 0
	v_add_u32_e32 v10, -1, v42
	v_fma_f32 v87, -v10, v42, v11
	v_cmp_ge_f32_e64 s[6:7], 0, v87
	v_add_u32_e32 v87, 1, v42
	s_nop 0
	v_cndmask_b32_e64 v10, v42, v10, s[6:7]
	v_fma_f32 v42, -v87, v42, v11
	v_cmp_lt_f32_e64 s[6:7], 0, v42
	s_nop 1
	v_cndmask_b32_e64 v10, v10, v87, s[6:7]
	v_mul_f32_e32 v42, 0x37800000, v10
	v_cndmask_b32_e32 v10, v10, v42, vcc
	v_cmp_class_f32_e32 vcc, v11, v44
	s_nop 1
	v_cndmask_b32_e32 v42, v10, v11, vcc
	v_div_scale_f32 v87, s[6:7], v42, v42, 1.0
	v_rcp_f32_e32 v88, v87
	v_lshlrev_b64 v[10:11], 11, v[40:41]
	v_lshl_add_u64 v[10:11], v[22:23], 0, v[10:11]
	global_store_short v[10:11], v43, off
	v_fma_f32 v10, -v87, v88, 1.0
	v_fmac_f32_e32 v88, v10, v88
	v_div_scale_f32 v10, vcc, 1.0, v42, 1.0
	v_mul_f32_e32 v11, v10, v88
	v_fma_f32 v40, -v87, v11, v10
	v_fmac_f32_e32 v11, v40, v88
	v_fma_f32 v10, -v87, v11, v10
	v_div_fmas_f32 v10, v10, v88, v11
	v_div_fixup_f32 v10, v10, v42, 1.0
	v_mul_f32_e32 v10, v12, v10
	s_nop 1
	v_add_f32_dpp v11, v13, v13 quad_perm:[1,0,3,2] row_mask:0xf bank_mask:0xf
	v_fma_f32 v10, v50, v10, v51
	v_fmac_f32_e32 v10, v86, v90
	s_nop 1
	v_add_f32_dpp v11, v11, v11 quad_perm:[2,3,0,1] row_mask:0xf bank_mask:0xf
	v_mul_f32_e32 v10, v10, v92
	v_cvt_pk_bf16_f32 v40, v10, s0
	s_nop 1
	v_add_f32_dpp v11, v11, v11 row_half_mirror row_mask:0xf bank_mask:0xf
	s_nop 1
	v_add_f32_dpp v11, v11, v11 row_mirror row_mask:0xf bank_mask:0xf
	s_nop 0
	s_nop 1
	v_add_f32_dpp v11, v11, v11 row_bcast:15 row_mask:0xa bank_mask:0xf
	s_nop 1
	v_add_f32_dpp v11, v11, v11 row_bcast:31 row_mask:0xc bank_mask:0xf
	s_nop 1
	v_readlane_b32 s6, v11, 63
	v_mov_b32_e32 v11, s6
	v_fmac_f32_e32 v13, 0xbc800000, v11
	v_mul_f32_e32 v11, v13, v13
	s_nop 1
	v_mov_b32_dpp v11, v11 quad_perm:[1,0,3,2] row_mask:0xf bank_mask:0xf
	v_fmac_f32_e32 v11, v13, v13
	s_nop 1
	v_add_f32_dpp v11, v11, v11 quad_perm:[2,3,0,1] row_mask:0xf bank_mask:0xf
	s_nop 1
	v_add_f32_dpp v11, v11, v11 row_half_mirror row_mask:0xf bank_mask:0xf
	s_nop 1
	v_add_f32_dpp v11, v11, v11 row_mirror row_mask:0xf bank_mask:0xf
	s_nop 0
	s_nop 1
	v_add_f32_dpp v11, v11, v11 row_bcast:15 row_mask:0xa bank_mask:0xf
	s_nop 1
	v_add_f32_dpp v11, v11, v11 row_bcast:31 row_mask:0xc bank_mask:0xf
	s_nop 1
	v_readlane_b32 s6, v11, 63
	v_mov_b32_e32 v11, s6
	v_fmamk_f32 v11, v11, 0x3c800000, v1
	v_mul_f32_e32 v12, 0x4f800000, v11
	v_cmp_gt_f32_e32 vcc, s48, v11
	s_nop 1
	v_cndmask_b32_e32 v11, v11, v12, vcc
	v_sqrt_f32_e32 v12, v11
	s_nop 0
	v_add_u32_e32 v10, -1, v12
	v_fma_f32 v41, -v10, v12, v11
	v_cmp_ge_f32_e64 s[6:7], 0, v41
	v_add_u32_e32 v41, 1, v12
	s_nop 0
	v_cndmask_b32_e64 v10, v12, v10, s[6:7]
	v_fma_f32 v12, -v41, v12, v11
	v_cmp_lt_f32_e64 s[6:7], 0, v12
	s_nop 1
	v_cndmask_b32_e64 v10, v10, v41, s[6:7]
	v_mul_f32_e32 v12, 0x37800000, v10
	v_cndmask_b32_e32 v10, v10, v12, vcc
	v_cmp_class_f32_e32 vcc, v11, v44
	s_nop 1
	v_cndmask_b32_e32 v12, v10, v11, vcc
	v_div_scale_f32 v41, s[6:7], v12, v12, 1.0
	v_rcp_f32_e32 v42, v41
	v_lshlrev_b64 v[10:11], 11, v[38:39]
	v_lshl_add_u64 v[10:11], v[22:23], 0, v[10:11]
	global_store_short v[10:11], v40, off
	v_fma_f32 v10, -v41, v42, 1.0
	v_fmac_f32_e32 v42, v10, v42
	v_div_scale_f32 v10, vcc, 1.0, v12, 1.0
	v_mul_f32_e32 v38, v10, v42
	v_fma_f32 v11, -v41, v38, v10
	v_fmac_f32_e32 v38, v11, v42
	v_fma_f32 v39, -v41, v38, v10
	v_add_u32_e32 v10, 0x4800, v79
	ds_read2_b32 v[10:11], v10 offset0:16 offset1:84
	v_div_fmas_f32 v38, v39, v42, v38
	v_div_fixup_f32 v12, v38, v12, 1.0
	v_mul_f32_e32 v12, v13, v12
	v_fma_f32 v12, v50, v12, v51
	s_waitcnt lgkmcnt(0)
; __device__ __forceinline__ bf16_t f2bf(float f) { return (bf16_t)(pk2(f, 0.f) & 0xffffu); }
; __device__ __forceinline__ float wave_sum(float v) {
;     v += dpp_f(v, 0); v += dpp_f(v, 1); v += dpp_f(v, 2); v += dpp_f(v, 3);
;     const int vi = __float_as_int(v);
;     const float s0 = __int_as_float(__builtin_amdgcn_readlane(vi, 0)), s1 = __int_as_float(__builtin_amdgcn_readlane(vi, 16)), s2 = __int_as_float(__builtin_amdgcn_readlane(vi, 32)), s3 = __int_as_float(__builtin_amdgcn_readlane(vi, 48));
;     return (s0 + s1) + (s2 + s3);
; __device__ __forceinline__ void rwkv_phase_c(const Ctx& C) {
;     ...
;             for (int u = 0; u < 8; ++u) {
;                 const int t = tg8 * 8 + u, tok = tok0 + t;
;                 const float y = MAT(1)[t * MS + ci];
;                 const float mean = wave_sum(y) * (1.0f / 64.0f); const float dlt = y - mean;
;                 const float var = wave_sum(dlt * dlt) * (1.0f / 64.0f);
;                 const float yn = dlt * (1.0f / sqrtf(var + 64e-5f)) * gg + gb;
;                 ycat[(size_t)tok * D_ + h * 64 + ci] = f2bf((yn + bo[u] * vv[u]) * gt[u]);
;             }
	v_fmac_f32_e32 v12, v85, v93
	v_mul_f32_e32 v12, v12, v94
	s_nop 1
	v_add_f32_dpp v13, v10, v10 quad_perm:[1,0,3,2] row_mask:0xf bank_mask:0xf
	v_cvt_pk_bf16_f32 v39, v12, s0
	s_nop 0
	s_nop 1
	v_add_f32_dpp v13, v13, v13 quad_perm:[2,3,0,1] row_mask:0xf bank_mask:0xf
	s_nop 1
	v_add_f32_dpp v13, v13, v13 row_half_mirror row_mask:0xf bank_mask:0xf
	s_nop 1
	v_add_f32_dpp v13, v13, v13 row_mirror row_mask:0xf bank_mask:0xf
	s_nop 0
	s_nop 1
	v_add_f32_dpp v13, v13, v13 row_bcast:15 row_mask:0xa bank_mask:0xf
	s_nop 1
	v_add_f32_dpp v13, v13, v13 row_bcast:31 row_mask:0xc bank_mask:0xf
	s_nop 1
	v_readlane_b32 s6, v13, 63
	v_mov_b32_e32 v13, s6
	v_fmamk_f32 v10, v13, 0xbc800000, v10
	v_mul_f32_e32 v13, v10, v10
	s_nop 1
	v_mov_b32_dpp v13, v13 quad_perm:[1,0,3,2] row_mask:0xf bank_mask:0xf
	v_fmac_f32_e32 v13, v10, v10
	s_nop 1
	v_add_f32_dpp v13, v13, v13 quad_perm:[2,3,0,1] row_mask:0xf bank_mask:0xf
	s_nop 1
	v_add_f32_dpp v13, v13, v13 row_half_mirror row_mask:0xf bank_mask:0xf
	s_nop 1
	v_add_f32_dpp v13, v13, v13 row_mirror row_mask:0xf bank_mask:0xf
	s_nop 0
	s_nop 1
	v_add_f32_dpp v13, v13, v13 row_bcast:15 row_mask:0xa bank_mask:0xf
	s_nop 1
	v_add_f32_dpp v13, v13, v13 row_bcast:31 row_mask:0xc bank_mask:0xf
	s_nop 1
	v_readlane_b32 s6, v13, 63
	v_mov_b32_e32 v13, s6
	v_fmamk_f32 v13, v13, 0x3c800000, v1
	v_mul_f32_e32 v38, 0x4f800000, v13
	v_cmp_gt_f32_e32 vcc, s48, v13
	s_nop 1
	v_cndmask_b32_e32 v13, v13, v38, vcc
	v_sqrt_f32_e32 v38, v13
	s_nop 0
	v_add_u32_e32 v12, -1, v38
	v_fma_f32 v40, -v12, v38, v13
	v_cmp_ge_f32_e64 s[6:7], 0, v40
	v_add_u32_e32 v40, 1, v38
	s_nop 0
	v_cndmask_b32_e64 v12, v38, v12, s[6:7]
	v_fma_f32 v38, -v40, v38, v13
	v_cmp_lt_f32_e64 s[6:7], 0, v38
	s_nop 1
	v_cndmask_b32_e64 v12, v12, v40, s[6:7]
	v_mul_f32_e32 v38, 0x37800000, v12
	v_cndmask_b32_e32 v12, v12, v38, vcc
	v_cmp_class_f32_e32 vcc, v13, v44
	s_nop 1
	v_cndmask_b32_e32 v38, v12, v13, vcc
	v_div_scale_f32 v40, s[6:7], v38, v38, 1.0
	v_rcp_f32_e32 v41, v40
	v_lshlrev_b64 v[12:13], 11, v[36:37]
	v_lshl_add_u64 v[12:13], v[22:23], 0, v[12:13]
	global_store_short v[12:13], v39, off
	v_fma_f32 v12, -v40, v41, 1.0
	v_fmac_f32_e32 v41, v12, v41
	v_div_scale_f32 v12, vcc, 1.0, v38, 1.0
	v_mul_f32_e32 v13, v12, v41
	v_fma_f32 v36, -v40, v13, v12
	v_fmac_f32_e32 v13, v36, v41
	v_fma_f32 v12, -v40, v13, v12
	v_div_fmas_f32 v12, v12, v41, v13
	v_div_fixup_f32 v12, v12, v38, 1.0
	v_mul_f32_e32 v10, v10, v12
	v_fma_f32 v10, v50, v10, v51
	v_fmac_f32_e32 v10, v84, v8
	s_nop 1
	v_add_f32_dpp v12, v11, v11 quad_perm:[1,0,3,2] row_mask:0xf bank_mask:0xf
	v_mul_f32_e32 v8, v10, v9
	v_cvt_pk_bf16_f32 v10, v8, s0
	s_nop 1
	v_add_f32_dpp v12, v12, v12 quad_perm:[2,3,0,1] row_mask:0xf bank_mask:0xf
	s_nop 1
	v_add_f32_dpp v12, v12, v12 row_half_mirror row_mask:0xf bank_mask:0xf
	s_nop 1
	v_add_f32_dpp v12, v12, v12 row_mirror row_mask:0xf bank_mask:0xf
	s_nop 0
	s_nop 1
	v_add_f32_dpp v12, v12, v12 row_bcast:15 row_mask:0xa bank_mask:0xf
	s_nop 1
	v_add_f32_dpp v12, v12, v12 row_bcast:31 row_mask:0xc bank_mask:0xf
	s_nop 1
	v_readlane_b32 s6, v12, 63
	v_mov_b32_e32 v12, s6
	v_fmac_f32_e32 v11, 0xbc800000, v12
	v_mul_f32_e32 v12, v11, v11
	s_nop 1
	v_mov_b32_dpp v12, v12 quad_perm:[1,0,3,2] row_mask:0xf bank_mask:0xf
	v_fmac_f32_e32 v12, v11, v11
	s_nop 1
	v_add_f32_dpp v12, v12, v12 quad_perm:[2,3,0,1] row_mask:0xf bank_mask:0xf
	s_nop 1
	v_add_f32_dpp v12, v12, v12 row_half_mirror row_mask:0xf bank_mask:0xf
	s_nop 1
	v_add_f32_dpp v12, v12, v12 row_mirror row_mask:0xf bank_mask:0xf
	s_nop 0
	s_nop 1
	v_add_f32_dpp v12, v12, v12 row_bcast:15 row_mask:0xa bank_mask:0xf
	s_nop 1
	v_add_f32_dpp v12, v12, v12 row_bcast:31 row_mask:0xc bank_mask:0xf
	s_nop 1
	v_readlane_b32 s6, v12, 63
	v_mov_b32_e32 v12, s6
	v_fmamk_f32 v12, v12, 0x3c800000, v1
	v_mul_f32_e32 v13, 0x4f800000, v12
	v_cmp_gt_f32_e32 vcc, s48, v12
	s_nop 1
	v_cndmask_b32_e32 v12, v12, v13, vcc
	v_sqrt_f32_e32 v13, v12
	s_nop 0
	v_add_u32_e32 v8, -1, v13
	v_fma_f32 v9, -v8, v13, v12
	v_cmp_ge_f32_e64 s[6:7], 0, v9
	v_add_u32_e32 v9, 1, v13
	s_nop 0
	v_cndmask_b32_e64 v8, v13, v8, s[6:7]
	v_fma_f32 v13, -v9, v13, v12
	v_cmp_lt_f32_e64 s[6:7], 0, v13
	s_nop 1
	v_cndmask_b32_e64 v8, v8, v9, s[6:7]
	v_mul_f32_e32 v9, 0x37800000, v8
	v_cndmask_b32_e32 v8, v8, v9, vcc
	v_cmp_class_f32_e32 vcc, v12, v44
	s_nop 1
	v_cndmask_b32_e32 v12, v8, v12, vcc
	v_div_scale_f32 v13, s[6:7], v12, v12, 1.0
	v_rcp_f32_e32 v36, v13
	v_lshlrev_b64 v[8:9], 11, v[34:35]
	v_lshl_add_u64 v[8:9], v[22:23], 0, v[8:9]
	global_store_short v[8:9], v10, off
	v_fma_f32 v8, -v13, v36, 1.0
	v_fmac_f32_e32 v36, v8, v36
	v_div_scale_f32 v8, vcc, 1.0, v12, 1.0
	v_mul_f32_e32 v9, v8, v36
	v_fma_f32 v10, -v13, v9, v8
	v_fmac_f32_e32 v9, v10, v36
	v_fma_f32 v8, -v13, v9, v8
	v_div_fmas_f32 v8, v8, v36, v9
	ds_read_b32 v9, v79 offset:19040
	ds_read_b32 v10, v80 offset:17408
	v_div_fixup_f32 v8, v8, v12, 1.0
	v_mul_f32_e32 v8, v11, v8
	v_fma_f32 v8, v50, v8, v51
	s_waitcnt lgkmcnt(1)
; __device__ __forceinline__ bf16_t f2bf(float f) { return (bf16_t)(pk2(f, 0.f) & 0xffffu); }
; __device__ __forceinline__ float wave_sum(float v) {
;     v += dpp_f(v, 0); v += dpp_f(v, 1); v += dpp_f(v, 2); v += dpp_f(v, 3);
;     const int vi = __float_as_int(v);
;     const float s0 = __int_as_float(__builtin_amdgcn_readlane(vi, 0)), s1 = __int_as_float(__builtin_amdgcn_readlane(vi, 16)), s2 = __int_as_float(__builtin_amdgcn_readlane(vi, 32)), s3 = __int_as_float(__builtin_amdgcn_readlane(vi, 48));
;     return (s0 + s1) + (s2 + s3);
; __device__ __forceinline__ void rwkv_phase_c(const Ctx& C) {
;     ...
;             for (int u = 0; u < 8; ++u) {
;                 const int t = tg8 * 8 + u, tok = tok0 + t;
;                 const float y = MAT(1)[t * MS + ci];
;                 const float mean = wave_sum(y) * (1.0f / 64.0f); const float dlt = y - mean;
;                 const float var = wave_sum(dlt * dlt) * (1.0f / 64.0f);
;                 const float yn = dlt * (1.0f / sqrtf(var + 64e-5f)) * gg + gb;
;                 ycat[(size_t)tok * D_ + h * 64 + ci] = f2bf((yn + bo[u] * vv[u]) * gt[u]);
;             }
;             __syncthreads();
	v_fmac_f32_e32 v8, v82, v6
	v_mul_f32_e32 v6, v8, v7
	s_nop 1
	v_add_f32_dpp v11, v9, v9 quad_perm:[1,0,3,2] row_mask:0xf bank_mask:0xf
	v_cvt_pk_bf16_f32 v8, v6, s0
	s_nop 0
	s_nop 1
	v_add_f32_dpp v11, v11, v11 quad_perm:[2,3,0,1] row_mask:0xf bank_mask:0xf
	s_nop 1
	v_add_f32_dpp v11, v11, v11 row_half_mirror row_mask:0xf bank_mask:0xf
	s_nop 1
	v_add_f32_dpp v11, v11, v11 row_mirror row_mask:0xf bank_mask:0xf
	s_nop 0
	s_nop 1
	v_add_f32_dpp v11, v11, v11 row_bcast:15 row_mask:0xa bank_mask:0xf
	s_nop 1
	v_add_f32_dpp v11, v11, v11 row_bcast:31 row_mask:0xc bank_mask:0xf
	s_nop 1
	v_readlane_b32 s6, v11, 63
	v_mov_b32_e32 v11, s6
	v_fmac_f32_e32 v9, 0xbc800000, v11
	v_mul_f32_e32 v11, v9, v9
	s_nop 1
	v_mov_b32_dpp v11, v11 quad_perm:[1,0,3,2] row_mask:0xf bank_mask:0xf
	v_fmac_f32_e32 v11, v9, v9
	s_nop 1
	v_add_f32_dpp v11, v11, v11 quad_perm:[2,3,0,1] row_mask:0xf bank_mask:0xf
	s_nop 1
	v_add_f32_dpp v11, v11, v11 row_half_mirror row_mask:0xf bank_mask:0xf
	s_nop 1
	v_add_f32_dpp v11, v11, v11 row_mirror row_mask:0xf bank_mask:0xf
	s_nop 0
	s_nop 1
	v_add_f32_dpp v11, v11, v11 row_bcast:15 row_mask:0xa bank_mask:0xf
	s_nop 1
	v_add_f32_dpp v11, v11, v11 row_bcast:31 row_mask:0xc bank_mask:0xf
	s_nop 1
	v_readlane_b32 s6, v11, 63
	v_mov_b32_e32 v11, s6
	v_fmamk_f32 v11, v11, 0x3c800000, v1
	v_mul_f32_e32 v12, 0x4f800000, v11
	v_cmp_gt_f32_e32 vcc, s48, v11
	s_nop 1
	v_cndmask_b32_e32 v11, v11, v12, vcc
	v_sqrt_f32_e32 v12, v11
	s_nop 0
	v_add_u32_e32 v6, -1, v12
	v_fma_f32 v7, -v6, v12, v11
	v_cmp_ge_f32_e64 s[6:7], 0, v7
	v_add_u32_e32 v7, 1, v12
	s_nop 0
	v_cndmask_b32_e64 v6, v12, v6, s[6:7]
	v_fma_f32 v12, -v7, v12, v11
	v_cmp_lt_f32_e64 s[6:7], 0, v12
	s_nop 1
	v_cndmask_b32_e64 v6, v6, v7, s[6:7]
	v_mul_f32_e32 v7, 0x37800000, v6
	v_cndmask_b32_e32 v6, v6, v7, vcc
	v_cmp_class_f32_e32 vcc, v11, v44
	s_nop 1
	v_cndmask_b32_e32 v11, v6, v11, vcc
	v_div_scale_f32 v12, s[6:7], v11, v11, 1.0
	v_rcp_f32_e32 v13, v12
	v_lshlrev_b64 v[6:7], 11, v[32:33]
	v_lshl_add_u64 v[6:7], v[22:23], 0, v[6:7]
	global_store_short v[6:7], v8, off
	v_fma_f32 v6, -v12, v13, 1.0
	v_fmac_f32_e32 v13, v6, v13
	v_div_scale_f32 v6, vcc, 1.0, v11, 1.0
	v_mul_f32_e32 v7, v6, v13
	v_fma_f32 v8, -v12, v7, v6
	v_fmac_f32_e32 v7, v8, v13
	v_fma_f32 v6, -v12, v7, v6
	v_div_fmas_f32 v6, v6, v13, v7
	v_div_fixup_f32 v6, v6, v11, 1.0
	v_mul_f32_e32 v6, v9, v6
	v_fma_f32 v6, v50, v6, v51
	v_fmac_f32_e32 v6, v83, v4
	s_waitcnt lgkmcnt(0)
	s_nop 1
	v_add_f32_dpp v4, v10, v10 quad_perm:[1,0,3,2] row_mask:0xf bank_mask:0xf
	s_nop 1
	v_add_f32_dpp v4, v4, v4 quad_perm:[2,3,0,1] row_mask:0xf bank_mask:0xf
	s_nop 1
	v_add_f32_dpp v4, v4, v4 row_half_mirror row_mask:0xf bank_mask:0xf
	s_nop 1
	v_add_f32_dpp v4, v4, v4 row_mirror row_mask:0xf bank_mask:0xf
	s_nop 0
	s_nop 1
	v_add_f32_dpp v4, v4, v4 row_bcast:15 row_mask:0xa bank_mask:0xf
	s_nop 1
	v_add_f32_dpp v4, v4, v4 row_bcast:31 row_mask:0xc bank_mask:0xf
	s_nop 1
	v_readlane_b32 s6, v4, 63
	v_mov_b32_e32 v4, s6
	v_fmac_f32_e32 v10, 0xbc800000, v4
	v_mul_f32_e32 v4, v10, v10
	s_nop 1
	v_mov_b32_dpp v4, v4 quad_perm:[1,0,3,2] row_mask:0xf bank_mask:0xf
	v_fmac_f32_e32 v4, v10, v10
	s_nop 1
	v_add_f32_dpp v4, v4, v4 quad_perm:[2,3,0,1] row_mask:0xf bank_mask:0xf
	s_nop 1
	v_add_f32_dpp v4, v4, v4 row_half_mirror row_mask:0xf bank_mask:0xf
	s_nop 1
	v_add_f32_dpp v4, v4, v4 row_mirror row_mask:0xf bank_mask:0xf
	s_nop 0
	s_nop 1
	v_add_f32_dpp v4, v4, v4 row_bcast:15 row_mask:0xa bank_mask:0xf
	s_nop 1
	v_add_f32_dpp v4, v4, v4 row_bcast:31 row_mask:0xc bank_mask:0xf
	s_nop 1
	v_readlane_b32 s6, v4, 63
	v_mov_b32_e32 v4, s6
	v_fmamk_f32 v4, v4, 0x3c800000, v1
	v_mul_f32_e32 v7, 0x4f800000, v4
	v_cmp_gt_f32_e32 vcc, s48, v4
	s_nop 1
	v_cndmask_b32_e32 v7, v4, v7, vcc
	v_sqrt_f32_e32 v8, v7
	v_mul_f32_e32 v4, v6, v5
	v_cvt_pk_bf16_f32 v6, v4, s0
	v_lshlrev_b64 v[4:5], 11, v[30:31]
	v_add_u32_e32 v9, -1, v8
	v_fma_f32 v11, -v9, v8, v7
	v_cmp_ge_f32_e64 s[6:7], 0, v11
	v_add_u32_e32 v11, 1, v8
	v_lshl_add_u64 v[4:5], v[22:23], 0, v[4:5]
	v_cndmask_b32_e64 v9, v8, v9, s[6:7]
	v_fma_f32 v8, -v11, v8, v7
	v_cmp_lt_f32_e64 s[6:7], 0, v8
	global_store_short v[4:5], v6, off
	v_add_u32_e32 v4, s54, v75
	v_cndmask_b32_e64 v8, v9, v11, s[6:7]
	v_mul_f32_e32 v9, 0x37800000, v8
	v_cndmask_b32_e32 v8, v8, v9, vcc
	v_cmp_class_f32_e32 vcc, v7, v44
	s_add_i32 s54, s54, 64
	s_cmpk_eq_i32 s54, 0x200
	v_cndmask_b32_e32 v7, v8, v7, vcc
	v_div_scale_f32 v8, s[6:7], v7, v7, 1.0
	v_rcp_f32_e32 v9, v8
	s_nop 0
	v_fma_f32 v5, -v8, v9, 1.0
	v_fmac_f32_e32 v9, v5, v9
	v_div_scale_f32 v5, vcc, 1.0, v7, 1.0
	v_mul_f32_e32 v6, v5, v9
	v_fma_f32 v11, -v8, v6, v5
	v_fmac_f32_e32 v6, v11, v9
	v_fma_f32 v5, -v8, v6, v5
	v_div_fmas_f32 v5, v5, v9, v6
	v_div_fixup_f32 v5, v5, v7, 1.0
	v_mul_f32_e32 v5, v10, v5
	v_fma_f32 v5, v50, v5, v51
	v_fmac_f32_e32 v5, v81, v2
	v_mul_f32_e32 v2, v5, v3
	v_ashrrev_i32_e32 v5, 31, v4
	v_cvt_pk_bf16_f32 v6, v2, s0
	v_lshlrev_b64 v[2:3], 11, v[4:5]
	v_lshl_add_u64 v[2:3], v[22:23], 0, v[2:3]
	global_store_short v[2:3], v6, off
	s_barrier
	s_cbranch_scc1 .LBB0_1060
